# XCD-local seams: up->dn and dn1->up2 seams skip the L2 writeback and the cross-XCD level (runtime check that wg%8 maps to one XCD, else global)
# speedup vs baseline: 1.0065x; 1.0065x over previous
; #define LAS __attribute__((address_space(3)))
; __device__ __forceinline__ unsigned xb_add(unsigned* p, unsigned v) { return __hip_atomic_fetch_add(p, v, __ATOMIC_RELAXED, __HIP_MEMORY_SCOPE_AGENT); }
; __device__ __forceinline__ unsigned xb_xcc_id() { return (unsigned)__builtin_amdgcn_s_getreg((3 << 11) | 20) & 0xFu; }
; __device__ __forceinline__ XcdBarrier xcd_barrier_post(unsigned* bar, volatile LAS unsigned* st) {
;     XcdBarrier b; b.bar = bar; b.x = xb_xcc_id(); b.st = st;
;     if (threadIdx.x == 0) (void)xb_add(&bar[XB_XCNT(b.x)], 1u);
;     return b;
; }
; __global__ void __launch_bounds__(NTHR) mk_fwd(Args args) {
;     __shared__ __attribute__((aligned(16))) unsigned char lds_raw[LDS_BYTES];
;     LAS unsigned char* lds = (LAS unsigned char*)lds_raw;
;     cg::grid_group grid = cg::this_grid();
;     const int tid = threadIdx.x, lane = tid & 63, wave = __builtin_amdgcn_readfirstlane(tid >> 6);
;     const int G = gridDim.x, gw = blockIdx.x * NWAVES + wave, NGW = G * NWAVES;
;     CArgs* ap = (CArgs*)__builtin_amdgcn_kernarg_segment_ptr();
;     ...
;     const int lo = ap->ph_lo, hi = ap->ph_hi;
;     ...
;     constexpr int lo = 0, hi = N_PHASES;
;     ...
;     int ph = 0;
;     ...
;     if (tid < 32) MISCP[tid] = 0u;
;     __syncthreads();
;     if (hi - lo > 1) (void)xcd_barrier_post((unsigned*)(ap->ws + ap->ws_off + WS_CTL), MISCP + 8);
_Z6mk_fwd4Args:
	s_load_dwordx2 s[14:15], s[0:1], 0xe0
	s_load_dword s46, s[0:1], 0xe8
	s_mov_b64 s[92:93], s[0:1]
	s_add_u32 s4, s92, 0xe0
	v_and_b32_e32 v145, 0x3ff, v0
	s_mov_b32 s96, s2
	s_addc_u32 s5, s93, 0
	v_readfirstlane_b32 s47, v145
	v_cmp_gt_u32_e32 vcc, 32, v145
	s_and_saveexec_b64 s[0:1], vcc
	v_mov_b32_e32 v1, 0x20140
	v_lshl_add_u32 v1, v145, 2, v1
	v_mov_b32_e32 v2, 0
	ds_write_b32 v1, v2
	v_writelane_b32 v252, s4, 0
	s_nop 1
	v_writelane_b32 v252, s5, 1
	s_or_b64 exec, exec, s[0:1]
	s_waitcnt lgkmcnt(0)
	s_barrier
	s_getreg_b32 s4, hwreg(HW_REG_XCC_ID, 0, 4)
	v_cmp_eq_u32_e64 s[2:3], 0, v145
	s_mov_b64 s[0:1], exec
	s_nop 0
	v_writelane_b32 v252, s2, 2
	s_nop 1
	v_writelane_b32 v252, s3, 3
	s_and_b64 s[2:3], s[0:1], s[2:3]
	s_mov_b64 exec, s[2:3]
	s_cbranch_execz .LBB0_5
	s_mov_b64 s[2:3], exec
	v_mbcnt_lo_u32_b32 v1, s2, 0
	v_mbcnt_hi_u32_b32 v1, s3, v1
	v_cmp_eq_u32_e32 vcc, 0, v1
	s_and_b64 s[6:7], exec, vcc
	s_mov_b64 exec, s[6:7]
	s_cbranch_execz .LBB0_5
	s_load_dwordx4 s[8:11], s[92:93], 0xc8
	v_mov_b32_e32 v1, 0x11500000
	s_waitcnt lgkmcnt(0)
	s_add_u32 s5, s8, s10
	s_addc_u32 s6, s9, s11
	s_mov_b32 s98, s5
	s_mov_b32 s99, s6
	s_sub_u32 s100, s4, s96
	s_and_b32 s100, s100, 7
	s_sub_u32 s101, 7, s100
	v_mov_b32_e32 v3, s100
	v_mov_b32_e32 v4, s101
	global_atomic_umax v3, v1, v3, s[98:99] offset:640 sc0
	global_atomic_umax v4, v1, v4, s[98:99] offset:704 sc0
	s_lshl_b32 s4, s4, 8
	s_and_b32 s4, s4, 0xf00
	s_add_u32 s4, s5, s4
	s_addc_u32 s5, s6, 0
	s_bcnt1_i32_b64 s2, s[2:3]
	v_mov_b32_e32 v2, s2
	global_atomic_add v1, v2, s[4:5] offset:1024
	s_waitcnt vmcnt(0)

; __global__ void __launch_bounds__(NTHR) mk_fwd(Args args) {
;     ...
;     if (hi - lo > 1) (void)xcd_barrier_post((unsigned*)(ap->ws + ap->ws_off + WS_CTL), MISCP + 8);
.LBB0_127:
	s_and_b64 exec, s[0:1], s[64:65]
	s_cbranch_execz .Lxl_s1_skip
	s_load_dwordx4 s[8:11], s[92:93], 0xc8
	v_mov_b32_e32 v0, 0x11500000
	s_waitcnt lgkmcnt(0)
	s_add_u32 s2, s8, s10
	s_addc_u32 s3, s9, s11
	global_load_dword v1, v0, s[2:3] offset:640 sc1
	global_load_dword v16, v0, s[2:3] offset:704 sc1
	s_waitcnt vmcnt(0)
	v_add_u32_e32 v1, v1, v16
	v_cmp_eq_u32_e32 vcc, 7, v1
	v_mov_b32_e32 v0, 0x20170
	v_cndmask_b32_e64 v1, 0, 1, vcc
	ds_write_b32 v0, v1
	s_waitcnt lgkmcnt(0)

; __device__ __forceinline__ unsigned xb_add(unsigned* p, unsigned v) { return __hip_atomic_fetch_add(p, v, __ATOMIC_RELAXED, __HIP_MEMORY_SCOPE_AGENT); }
; __device__ __forceinline__ void xcd_barrier(const XcdBarrier& b) {
;     asm volatile("s_waitcnt vmcnt(0)" ::: "memory");
;     __syncthreads();
;     if (threadIdx.x == 0) {
;         unsigned* bar = b.bar;
;         __builtin_amdgcn_s_waitcnt(0);
;         unsigned nloc = b.st[0], nx = b.st[1];
;         if (nloc == 0u) { xcd_barrier_complete(bar, b.x, nloc, nx); b.st[0] = nloc; b.st[1] = nx; }
;         const unsigned old = xb_add(&bar[XB_XSUB(b.x)], 1u);
;         const unsigned gen = old / nloc;
;         if (old + 1u == (gen + 1u) * nloc) {
;             __builtin_amdgcn_fence(__ATOMIC_RELEASE, "agent");
;             asm volatile("s_waitcnt vmcnt(0)" ::: "memory");
;             const unsigned og = xb_add(&bar[XB_TOP], 1u);
;             const unsigned tg = og / nx;
;             if (og + 1u == (tg + 1u) * nx) xb_add(&bar[XB_TOPGEN], 1u);
.LBB0_504:
	s_andn2_saveexec_b64 s[6:7], s[6:7]
	s_cbranch_execz .LBB0_524
	s_mov_b64 s[6:7], exec
	v_add_u32_e32 v2, 16, v194
	ds_read_b32 v2, v2
	v_readfirstlane_b32 s99, v1
	s_nop 3
	s_lshr_b32 s99, 0x21c2, s99
	s_waitcnt lgkmcnt(0)
	v_readfirstlane_b32 s98, v2
	s_nop 3
	s_and_b32 s99, s99, s98
	s_bitcmp1_b32 s99, 0
	s_cbranch_scc1 .Lxl0_local
	buffer_wbl2 sc1
	s_waitcnt lgkmcnt(0)
	s_waitcnt vmcnt(0)
	v_mbcnt_lo_u32_b32 v1, s6, 0
	v_mbcnt_hi_u32_b32 v1, s7, v1
	v_cmp_eq_u32_e32 vcc, 0, v1
	s_and_saveexec_b64 s[8:9], vcc
	s_cbranch_execz .LBB0_507
	s_bcnt1_i32_b64 s6, s[6:7]
	v_mov_b32_e32 v2, s6
	v_mov_b32_e32 v3, 0x11503000
	global_atomic_add v2, v3, v2, s[2:3] offset:1024 sc0

; __device__ __forceinline__ unsigned xb_add(unsigned* p, unsigned v) { return __hip_atomic_fetch_add(p, v, __ATOMIC_RELAXED, __HIP_MEMORY_SCOPE_AGENT); }
; __device__ __forceinline__ void xcd_barrier(const XcdBarrier& b) {
;     ...
;             __builtin_amdgcn_fence(__ATOMIC_ACQUIRE, "agent");
;             xb_add(&bar[XB_XGEN(b.x)], 1u);
;             asm volatile("s_waitcnt vmcnt(0)" ::: "memory");
.Lxl0_local:
	s_mov_b64 s[2:3], exec
	v_mbcnt_lo_u32_b32 v0, s2, 0
	v_mbcnt_hi_u32_b32 v0, s3, v0
	v_cmp_eq_u32_e32 vcc, 0, v0
	s_waitcnt vmcnt(0)
	s_and_saveexec_b64 s[6:7], vcc
	s_cbranch_execz .LBB0_523
	s_bcnt1_i32_b64 s2, s[2:3]
	v_mov_b32_e32 v0, s2
	global_atomic_add v197, v0, s[4:5] offset:1024
